# adds layer-0 out-proj epilogue rewrite (residual loads 3 groups ahead, half-row lane exchange for full-line f32 loads/stores)
# speedup vs baseline: 1.0671x; 1.0018x over previous
; #define LAS __attribute__((address_space(3)))
;     __device__ __forceinline__ void operator()(const f32x4 (&acc)[2][2][4][2], const Unit& u, int wr, int wc, int fr, int fq, LAS unsigned char* lds) const {
;         const int row0 = u.pm * BM + wr * 64 + fr; const int col0 = u.pn * BM + wc * 32 + 8 * fq;
;         LAS float* part = (LAS float*)(lds + 131072);
;         f32x4 gg[2][2];
; #pragma unroll
;         for (int bj = 0; bj < 2; ++bj)
; #pragma unroll
;             for (int n = 0; n < 2; ++n) gg[bj][n] = *(const f32x4*)(g + col0 + bj * HALF + 4 * n);
; #pragma unroll
;         for (int ai = 0; ai < 2; ++ai)
; #pragma unroll
;             for (int m = 0; m < 4; ++m) { const size_t ro = (size_t)(row0 + ai * HALF + m * 16) * ldc + col0; float ssq = 0.f;
; #pragma unroll
;                 for (int bj = 0; bj < 2; ++bj) { const size_t o = ro + bj * HALF;
;                     const f32x4 r0 = *(const f32x4*)(res + o), r1 = *(const f32x4*)(res + o + 4);
.LBB0_786:
	s_lshl_b32 s46, s4, 8
	v_readlane_b32 s4, v244, 0
	v_readlane_b32 s5, v244, 1
	v_and_b32_e32 v25, 8, v172
	v_sub_u32_e32 v26, v172, v25
	v_add_u32_e32 v26, s46, v26
	v_lshl_or_b32 v27, s56, 8, v174
	v_lshrrev_b32_e32 v25, 1, v25
	v_add_u32_e32 v27, v27, v25
	v_lshl_add_u32 v28, v26, 10, v27
	v_lshlrev_b32_e32 v170, 2, v28
	v_lshlrev_b32_e32 v247, 1, v28
	v_lshlrev_b32_e32 v27, 2, v27
	v_add_u32_e32 v171, 0x8000, v170
	v_add_u32_e32 v24, 0x4000, v247
	v_mov_b32_e32 v177, v170
	v_mov_b32_e32 v195, v171
	v_lshlrev_b32_e32 v54, 2, v193
	v_lshlrev_b32_e32 v55, 2, v194
	global_load_dwordx4 v[180:183], v27, s[4:5]
	global_load_dwordx4 v[166:169], v27, s[4:5] offset:512
	global_load_dwordx4 v[196:199], v170, s[80:81]
	global_load_dwordx4 v[200:203], v170, s[80:81] offset:512
	global_load_dwordx4 v[204:207], v171, s[80:81]
	global_load_dwordx4 v[208:211], v171, s[80:81] offset:512
	v_add_u32_e32 v170, 0x10000, v170
	v_add_u32_e32 v171, 0x10000, v171
	global_load_dwordx4 v[212:215], v170, s[80:81]
	global_load_dwordx4 v[216:219], v170, s[80:81] offset:512
	global_load_dwordx4 v[220:223], v171, s[80:81]
	global_load_dwordx4 v[224:227], v171, s[80:81] offset:512
	v_add_u32_e32 v170, 0x10000, v170
	v_add_u32_e32 v171, 0x10000, v171
	global_load_dwordx4 v[228:231], v170, s[80:81]
	global_load_dwordx4 v[232:235], v170, s[80:81] offset:512
	global_load_dwordx4 v[236:239], v171, s[80:81]
	global_load_dwordx4 v[240:243], v171, s[80:81] offset:512
	v_add_u32_e32 v170, 0x10000, v170
	v_add_u32_e32 v171, 0x10000, v171
	v_mov_b32_dpp v25, v140 row_ror:8 row_mask:0xf bank_mask:0xf
	v_mov_b32_dpp v26, v141 row_ror:8 row_mask:0xf bank_mask:0xf
	v_mov_b32_dpp v140, v136 row_ror:8 row_mask:0xf bank_mask:0xc
	v_mov_b32_dpp v141, v137 row_ror:8 row_mask:0xf bank_mask:0xc
	v_mov_b32_dpp v136, v25 quad_perm:[0,1,2,3] row_mask:0xf bank_mask:0x3
	v_mov_b32_dpp v137, v26 quad_perm:[0,1,2,3] row_mask:0xf bank_mask:0x3
	v_mov_b32_dpp v25, v142 row_ror:8 row_mask:0xf bank_mask:0xf
	v_mov_b32_dpp v26, v143 row_ror:8 row_mask:0xf bank_mask:0xf
	v_mov_b32_dpp v142, v138 row_ror:8 row_mask:0xf bank_mask:0xc
	v_mov_b32_dpp v143, v139 row_ror:8 row_mask:0xf bank_mask:0xc
	v_mov_b32_dpp v138, v25 quad_perm:[0,1,2,3] row_mask:0xf bank_mask:0x3
	v_mov_b32_dpp v139, v26 quad_perm:[0,1,2,3] row_mask:0xf bank_mask:0x3
	v_mov_b32_dpp v25, v132 row_ror:8 row_mask:0xf bank_mask:0xf
	v_mov_b32_dpp v26, v133 row_ror:8 row_mask:0xf bank_mask:0xf
	v_mov_b32_dpp v132, v128 row_ror:8 row_mask:0xf bank_mask:0xc
	v_mov_b32_dpp v133, v129 row_ror:8 row_mask:0xf bank_mask:0xc
	v_mov_b32_dpp v128, v25 quad_perm:[0,1,2,3] row_mask:0xf bank_mask:0x3
	v_mov_b32_dpp v129, v26 quad_perm:[0,1,2,3] row_mask:0xf bank_mask:0x3
	v_mov_b32_dpp v25, v134 row_ror:8 row_mask:0xf bank_mask:0xf
	v_mov_b32_dpp v26, v135 row_ror:8 row_mask:0xf bank_mask:0xf
	v_mov_b32_dpp v134, v130 row_ror:8 row_mask:0xf bank_mask:0xc
	v_mov_b32_dpp v135, v131 row_ror:8 row_mask:0xf bank_mask:0xc
	v_mov_b32_dpp v130, v25 quad_perm:[0,1,2,3] row_mask:0xf bank_mask:0x3
	v_mov_b32_dpp v131, v26 quad_perm:[0,1,2,3] row_mask:0xf bank_mask:0x3
	v_mov_b32_dpp v25, v124 row_ror:8 row_mask:0xf bank_mask:0xf
	v_mov_b32_dpp v26, v125 row_ror:8 row_mask:0xf bank_mask:0xf
	v_mov_b32_dpp v124, v120 row_ror:8 row_mask:0xf bank_mask:0xc
	v_mov_b32_dpp v125, v121 row_ror:8 row_mask:0xf bank_mask:0xc
	v_mov_b32_dpp v120, v25 quad_perm:[0,1,2,3] row_mask:0xf bank_mask:0x3
	v_mov_b32_dpp v121, v26 quad_perm:[0,1,2,3] row_mask:0xf bank_mask:0x3
	v_mov_b32_dpp v25, v126 row_ror:8 row_mask:0xf bank_mask:0xf
	v_mov_b32_dpp v26, v127 row_ror:8 row_mask:0xf bank_mask:0xf
	v_mov_b32_dpp v126, v122 row_ror:8 row_mask:0xf bank_mask:0xc
	v_mov_b32_dpp v127, v123 row_ror:8 row_mask:0xf bank_mask:0xc
	v_mov_b32_dpp v122, v25 quad_perm:[0,1,2,3] row_mask:0xf bank_mask:0x3
	v_mov_b32_dpp v123, v26 quad_perm:[0,1,2,3] row_mask:0xf bank_mask:0x3
	v_mov_b32_dpp v25, v116 row_ror:8 row_mask:0xf bank_mask:0xf
	v_mov_b32_dpp v26, v117 row_ror:8 row_mask:0xf bank_mask:0xf
	v_mov_b32_dpp v116, v112 row_ror:8 row_mask:0xf bank_mask:0xc
	v_mov_b32_dpp v117, v113 row_ror:8 row_mask:0xf bank_mask:0xc
	v_mov_b32_dpp v112, v25 quad_perm:[0,1,2,3] row_mask:0xf bank_mask:0x3
	v_mov_b32_dpp v113, v26 quad_perm:[0,1,2,3] row_mask:0xf bank_mask:0x3
	v_mov_b32_dpp v25, v118 row_ror:8 row_mask:0xf bank_mask:0xf
	v_mov_b32_dpp v26, v119 row_ror:8 row_mask:0xf bank_mask:0xf
	v_mov_b32_dpp v118, v114 row_ror:8 row_mask:0xf bank_mask:0xc
	v_mov_b32_dpp v119, v115 row_ror:8 row_mask:0xf bank_mask:0xc
	v_mov_b32_dpp v114, v25 quad_perm:[0,1,2,3] row_mask:0xf bank_mask:0x3
	v_mov_b32_dpp v115, v26 quad_perm:[0,1,2,3] row_mask:0xf bank_mask:0x3
	v_mov_b32_dpp v25, v108 row_ror:8 row_mask:0xf bank_mask:0xf
	v_mov_b32_dpp v26, v109 row_ror:8 row_mask:0xf bank_mask:0xf
	v_mov_b32_dpp v108, v104 row_ror:8 row_mask:0xf bank_mask:0xc
	v_mov_b32_dpp v109, v105 row_ror:8 row_mask:0xf bank_mask:0xc
	v_mov_b32_dpp v104, v25 quad_perm:[0,1,2,3] row_mask:0xf bank_mask:0x3
	v_mov_b32_dpp v105, v26 quad_perm:[0,1,2,3] row_mask:0xf bank_mask:0x3
	v_mov_b32_dpp v25, v110 row_ror:8 row_mask:0xf bank_mask:0xf
	v_mov_b32_dpp v26, v111 row_ror:8 row_mask:0xf bank_mask:0xf
	v_mov_b32_dpp v110, v106 row_ror:8 row_mask:0xf bank_mask:0xc
	v_mov_b32_dpp v111, v107 row_ror:8 row_mask:0xf bank_mask:0xc
	v_mov_b32_dpp v106, v25 quad_perm:[0,1,2,3] row_mask:0xf bank_mask:0x3
	v_mov_b32_dpp v107, v26 quad_perm:[0,1,2,3] row_mask:0xf bank_mask:0x3
	v_mov_b32_dpp v25, v100 row_ror:8 row_mask:0xf bank_mask:0xf
	v_mov_b32_dpp v26, v101 row_ror:8 row_mask:0xf bank_mask:0xf
	v_mov_b32_dpp v100, v96 row_ror:8 row_mask:0xf bank_mask:0xc
; __device__ __forceinline__ unsigned cvt_pk_bf16(float lo, float hi) { unsigned r; asm volatile("v_cvt_pk_bf16_f32 %0, %1, %2" : "=v"(r) : "v"(lo), "v"(hi)); return r; }
;     __device__ __forceinline__ void operator()(const f32x4 (&acc)[2][2][4][2], const Unit& u, int wr, int wc, int fr, int fq, LAS unsigned char* lds) const {
;     ...
;                 for (int bj = 0; bj < 2; ++bj) { const size_t o = ro + bj * HALF;
;                     const f32x4 r0 = *(const f32x4*)(res + o), r1 = *(const f32x4*)(res + o + 4);
;                     const f32x4 x0 = r0 + acc[ai][bj][m][0], x1 = r1 + acc[ai][bj][m][1];
;                     *(f32x4*)(O + o) = x0; *(f32x4*)(O + o + 4) = x1;
;                     u32x4 hb; hb.x = cvt_pk_bf16(x0[0] * gg[bj][0][0], x0[1] * gg[bj][0][1]); hb.y = cvt_pk_bf16(x0[2] * gg[bj][0][2], x0[3] * gg[bj][0][3]);
;                     hb.z = cvt_pk_bf16(x1[0] * gg[bj][1][0], x1[1] * gg[bj][1][1]); hb.w = cvt_pk_bf16(x1[2] * gg[bj][1][2], x1[3] * gg[bj][1][3]);
;                     *(u32x4*)(H + o) = hb;
	v_mov_b32_dpp v101, v97 row_ror:8 row_mask:0xf bank_mask:0xc
	v_mov_b32_dpp v96, v25 quad_perm:[0,1,2,3] row_mask:0xf bank_mask:0x3
	v_mov_b32_dpp v97, v26 quad_perm:[0,1,2,3] row_mask:0xf bank_mask:0x3
	v_mov_b32_dpp v25, v102 row_ror:8 row_mask:0xf bank_mask:0xf
	v_mov_b32_dpp v26, v103 row_ror:8 row_mask:0xf bank_mask:0xf
	v_mov_b32_dpp v102, v98 row_ror:8 row_mask:0xf bank_mask:0xc
	v_mov_b32_dpp v103, v99 row_ror:8 row_mask:0xf bank_mask:0xc
	v_mov_b32_dpp v98, v25 quad_perm:[0,1,2,3] row_mask:0xf bank_mask:0x3
	v_mov_b32_dpp v99, v26 quad_perm:[0,1,2,3] row_mask:0xf bank_mask:0x3
	v_mov_b32_dpp v25, v92 row_ror:8 row_mask:0xf bank_mask:0xf
	v_mov_b32_dpp v26, v93 row_ror:8 row_mask:0xf bank_mask:0xf
	v_mov_b32_dpp v92, v88 row_ror:8 row_mask:0xf bank_mask:0xc
	v_mov_b32_dpp v93, v89 row_ror:8 row_mask:0xf bank_mask:0xc
	v_mov_b32_dpp v88, v25 quad_perm:[0,1,2,3] row_mask:0xf bank_mask:0x3
	v_mov_b32_dpp v89, v26 quad_perm:[0,1,2,3] row_mask:0xf bank_mask:0x3
	v_mov_b32_dpp v25, v94 row_ror:8 row_mask:0xf bank_mask:0xf
	v_mov_b32_dpp v26, v95 row_ror:8 row_mask:0xf bank_mask:0xf
	v_mov_b32_dpp v94, v90 row_ror:8 row_mask:0xf bank_mask:0xc
	v_mov_b32_dpp v95, v91 row_ror:8 row_mask:0xf bank_mask:0xc
	v_mov_b32_dpp v90, v25 quad_perm:[0,1,2,3] row_mask:0xf bank_mask:0x3
	v_mov_b32_dpp v91, v26 quad_perm:[0,1,2,3] row_mask:0xf bank_mask:0x3
	v_mov_b32_dpp v25, v84 row_ror:8 row_mask:0xf bank_mask:0xf
	v_mov_b32_dpp v26, v85 row_ror:8 row_mask:0xf bank_mask:0xf
	v_mov_b32_dpp v84, v80 row_ror:8 row_mask:0xf bank_mask:0xc
	v_mov_b32_dpp v85, v81 row_ror:8 row_mask:0xf bank_mask:0xc
	v_mov_b32_dpp v80, v25 quad_perm:[0,1,2,3] row_mask:0xf bank_mask:0x3
	v_mov_b32_dpp v81, v26 quad_perm:[0,1,2,3] row_mask:0xf bank_mask:0x3
	v_mov_b32_dpp v25, v86 row_ror:8 row_mask:0xf bank_mask:0xf
	v_mov_b32_dpp v26, v87 row_ror:8 row_mask:0xf bank_mask:0xf
	v_mov_b32_dpp v86, v82 row_ror:8 row_mask:0xf bank_mask:0xc
	v_mov_b32_dpp v87, v83 row_ror:8 row_mask:0xf bank_mask:0xc
	v_mov_b32_dpp v82, v25 quad_perm:[0,1,2,3] row_mask:0xf bank_mask:0x3
	v_mov_b32_dpp v83, v26 quad_perm:[0,1,2,3] row_mask:0xf bank_mask:0x3
	v_mov_b32_dpp v25, v76 row_ror:8 row_mask:0xf bank_mask:0xf
	v_mov_b32_dpp v26, v77 row_ror:8 row_mask:0xf bank_mask:0xf
	v_mov_b32_dpp v76, v72 row_ror:8 row_mask:0xf bank_mask:0xc
	v_mov_b32_dpp v77, v73 row_ror:8 row_mask:0xf bank_mask:0xc
	v_mov_b32_dpp v72, v25 quad_perm:[0,1,2,3] row_mask:0xf bank_mask:0x3
	v_mov_b32_dpp v73, v26 quad_perm:[0,1,2,3] row_mask:0xf bank_mask:0x3
	v_mov_b32_dpp v25, v78 row_ror:8 row_mask:0xf bank_mask:0xf
	v_mov_b32_dpp v26, v79 row_ror:8 row_mask:0xf bank_mask:0xf
	v_mov_b32_dpp v78, v74 row_ror:8 row_mask:0xf bank_mask:0xc
	v_mov_b32_dpp v79, v75 row_ror:8 row_mask:0xf bank_mask:0xc
	v_mov_b32_dpp v74, v25 quad_perm:[0,1,2,3] row_mask:0xf bank_mask:0x3
	v_mov_b32_dpp v75, v26 quad_perm:[0,1,2,3] row_mask:0xf bank_mask:0x3
	v_mov_b32_dpp v25, v68 row_ror:8 row_mask:0xf bank_mask:0xf
	v_mov_b32_dpp v26, v69 row_ror:8 row_mask:0xf bank_mask:0xf
	v_mov_b32_dpp v68, v64 row_ror:8 row_mask:0xf bank_mask:0xc
	v_mov_b32_dpp v69, v65 row_ror:8 row_mask:0xf bank_mask:0xc
	v_mov_b32_dpp v64, v25 quad_perm:[0,1,2,3] row_mask:0xf bank_mask:0x3
	v_mov_b32_dpp v65, v26 quad_perm:[0,1,2,3] row_mask:0xf bank_mask:0x3
	v_mov_b32_dpp v25, v70 row_ror:8 row_mask:0xf bank_mask:0xf
	v_mov_b32_dpp v26, v71 row_ror:8 row_mask:0xf bank_mask:0xf
	v_mov_b32_dpp v70, v66 row_ror:8 row_mask:0xf bank_mask:0xc
	v_mov_b32_dpp v71, v67 row_ror:8 row_mask:0xf bank_mask:0xc
	v_mov_b32_dpp v66, v25 quad_perm:[0,1,2,3] row_mask:0xf bank_mask:0x3
	v_mov_b32_dpp v67, v26 quad_perm:[0,1,2,3] row_mask:0xf bank_mask:0x3
	v_mov_b32_dpp v25, v60 row_ror:8 row_mask:0xf bank_mask:0xf
	v_mov_b32_dpp v26, v61 row_ror:8 row_mask:0xf bank_mask:0xf
	v_mov_b32_dpp v60, v56 row_ror:8 row_mask:0xf bank_mask:0xc
	v_mov_b32_dpp v61, v57 row_ror:8 row_mask:0xf bank_mask:0xc
	v_mov_b32_dpp v56, v25 quad_perm:[0,1,2,3] row_mask:0xf bank_mask:0x3
	v_mov_b32_dpp v57, v26 quad_perm:[0,1,2,3] row_mask:0xf bank_mask:0x3
	v_mov_b32_dpp v25, v62 row_ror:8 row_mask:0xf bank_mask:0xf
	v_mov_b32_dpp v26, v63 row_ror:8 row_mask:0xf bank_mask:0xf
	v_mov_b32_dpp v62, v58 row_ror:8 row_mask:0xf bank_mask:0xc
	v_mov_b32_dpp v63, v59 row_ror:8 row_mask:0xf bank_mask:0xc
	v_mov_b32_dpp v58, v25 quad_perm:[0,1,2,3] row_mask:0xf bank_mask:0x3
	v_mov_b32_dpp v59, v26 quad_perm:[0,1,2,3] row_mask:0xf bank_mask:0x3
	v_mov_b32_dpp v25, v44 row_ror:8 row_mask:0xf bank_mask:0xf
	v_mov_b32_dpp v26, v45 row_ror:8 row_mask:0xf bank_mask:0xf
	v_mov_b32_dpp v44, v40 row_ror:8 row_mask:0xf bank_mask:0xc
	v_mov_b32_dpp v45, v41 row_ror:8 row_mask:0xf bank_mask:0xc
	v_mov_b32_dpp v40, v25 quad_perm:[0,1,2,3] row_mask:0xf bank_mask:0x3
	v_mov_b32_dpp v41, v26 quad_perm:[0,1,2,3] row_mask:0xf bank_mask:0x3
	v_mov_b32_dpp v25, v46 row_ror:8 row_mask:0xf bank_mask:0xf
	v_mov_b32_dpp v26, v47 row_ror:8 row_mask:0xf bank_mask:0xf
	v_mov_b32_dpp v46, v42 row_ror:8 row_mask:0xf bank_mask:0xc
	v_mov_b32_dpp v47, v43 row_ror:8 row_mask:0xf bank_mask:0xc
	v_mov_b32_dpp v42, v25 quad_perm:[0,1,2,3] row_mask:0xf bank_mask:0x3
	v_mov_b32_dpp v43, v26 quad_perm:[0,1,2,3] row_mask:0xf bank_mask:0x3
	v_mov_b32_dpp v25, v36 row_ror:8 row_mask:0xf bank_mask:0xf
	v_mov_b32_dpp v26, v37 row_ror:8 row_mask:0xf bank_mask:0xf
	v_mov_b32_dpp v36, v32 row_ror:8 row_mask:0xf bank_mask:0xc
	v_mov_b32_dpp v37, v33 row_ror:8 row_mask:0xf bank_mask:0xc
	v_mov_b32_dpp v32, v25 quad_perm:[0,1,2,3] row_mask:0xf bank_mask:0x3
	v_mov_b32_dpp v33, v26 quad_perm:[0,1,2,3] row_mask:0xf bank_mask:0x3
; __device__ __forceinline__ unsigned cvt_pk_bf16(float lo, float hi) { unsigned r; asm volatile("v_cvt_pk_bf16_f32 %0, %1, %2" : "=v"(r) : "v"(lo), "v"(hi)); return r; }
;     __device__ __forceinline__ void operator()(const f32x4 (&acc)[2][2][4][2], const Unit& u, int wr, int wc, int fr, int fq, LAS unsigned char* lds) const {
;     ...
;                 for (int bj = 0; bj < 2; ++bj) { const size_t o = ro + bj * HALF;
;                     const f32x4 r0 = *(const f32x4*)(res + o), r1 = *(const f32x4*)(res + o + 4);
;                     const f32x4 x0 = r0 + acc[ai][bj][m][0], x1 = r1 + acc[ai][bj][m][1];
;                     *(f32x4*)(O + o) = x0; *(f32x4*)(O + o + 4) = x1;
;                     u32x4 hb; hb.x = cvt_pk_bf16(x0[0] * gg[bj][0][0], x0[1] * gg[bj][0][1]); hb.y = cvt_pk_bf16(x0[2] * gg[bj][0][2], x0[3] * gg[bj][0][3]);
;                     hb.z = cvt_pk_bf16(x1[0] * gg[bj][1][0], x1[1] * gg[bj][1][1]); hb.w = cvt_pk_bf16(x1[2] * gg[bj][1][2], x1[3] * gg[bj][1][3]);
;                     *(u32x4*)(H + o) = hb;
;                     ssq += ((x0[0] * x0[0] + x0[1] * x0[1]) + (x0[2] * x0[2] + x0[3] * x0[3])) + ((x1[0] * x1[0] + x1[1] * x1[1]) + (x1[2] * x1[2] + x1[3] * x1[3])); }
;                 ssq += __shfl_xor(ssq, 16); ssq += __shfl_xor(ssq, 32);
;                 if (fq == 0) part[(ai * HALF + wr * 64 + m * 16 + fr) * 4 + wc] = ssq; }
	v_mov_b32_dpp v25, v38 row_ror:8 row_mask:0xf bank_mask:0xf
	v_mov_b32_dpp v26, v39 row_ror:8 row_mask:0xf bank_mask:0xf
	v_mov_b32_dpp v38, v34 row_ror:8 row_mask:0xf bank_mask:0xc
	v_mov_b32_dpp v39, v35 row_ror:8 row_mask:0xf bank_mask:0xc
	v_mov_b32_dpp v34, v25 quad_perm:[0,1,2,3] row_mask:0xf bank_mask:0x3
	v_mov_b32_dpp v35, v26 quad_perm:[0,1,2,3] row_mask:0xf bank_mask:0x3
	v_mov_b32_dpp v25, v20 row_ror:8 row_mask:0xf bank_mask:0xf
	v_mov_b32_dpp v26, v21 row_ror:8 row_mask:0xf bank_mask:0xf
	v_mov_b32_dpp v20, v16 row_ror:8 row_mask:0xf bank_mask:0xc
	v_mov_b32_dpp v21, v17 row_ror:8 row_mask:0xf bank_mask:0xc
	v_mov_b32_dpp v16, v25 quad_perm:[0,1,2,3] row_mask:0xf bank_mask:0x3
	v_mov_b32_dpp v17, v26 quad_perm:[0,1,2,3] row_mask:0xf bank_mask:0x3
	v_mov_b32_dpp v25, v22 row_ror:8 row_mask:0xf bank_mask:0xf
	v_mov_b32_dpp v26, v23 row_ror:8 row_mask:0xf bank_mask:0xf
	v_mov_b32_dpp v22, v18 row_ror:8 row_mask:0xf bank_mask:0xc
	v_mov_b32_dpp v23, v19 row_ror:8 row_mask:0xf bank_mask:0xc
	v_mov_b32_dpp v18, v25 quad_perm:[0,1,2,3] row_mask:0xf bank_mask:0x3
	v_mov_b32_dpp v19, v26 quad_perm:[0,1,2,3] row_mask:0xf bank_mask:0x3
	v_mov_b32_dpp v25, v12 row_ror:8 row_mask:0xf bank_mask:0xf
	v_mov_b32_dpp v26, v13 row_ror:8 row_mask:0xf bank_mask:0xf
	v_mov_b32_dpp v12, v8 row_ror:8 row_mask:0xf bank_mask:0xc
	v_mov_b32_dpp v13, v9 row_ror:8 row_mask:0xf bank_mask:0xc
	v_mov_b32_dpp v8, v25 quad_perm:[0,1,2,3] row_mask:0xf bank_mask:0x3
	v_mov_b32_dpp v9, v26 quad_perm:[0,1,2,3] row_mask:0xf bank_mask:0x3
	v_mov_b32_dpp v25, v14 row_ror:8 row_mask:0xf bank_mask:0xf
	v_mov_b32_dpp v26, v15 row_ror:8 row_mask:0xf bank_mask:0xf
	v_mov_b32_dpp v14, v10 row_ror:8 row_mask:0xf bank_mask:0xc
	v_mov_b32_dpp v15, v11 row_ror:8 row_mask:0xf bank_mask:0xc
	v_mov_b32_dpp v10, v25 quad_perm:[0,1,2,3] row_mask:0xf bank_mask:0x3
	v_mov_b32_dpp v11, v26 quad_perm:[0,1,2,3] row_mask:0xf bank_mask:0x3
	v_mov_b32_dpp v25, v4 row_ror:8 row_mask:0xf bank_mask:0xf
	v_mov_b32_dpp v26, v5 row_ror:8 row_mask:0xf bank_mask:0xf
	v_mov_b32_dpp v4, v0 row_ror:8 row_mask:0xf bank_mask:0xc
	v_mov_b32_dpp v5, v1 row_ror:8 row_mask:0xf bank_mask:0xc
	v_mov_b32_dpp v0, v25 quad_perm:[0,1,2,3] row_mask:0xf bank_mask:0x3
	v_mov_b32_dpp v1, v26 quad_perm:[0,1,2,3] row_mask:0xf bank_mask:0x3
	v_mov_b32_dpp v25, v6 row_ror:8 row_mask:0xf bank_mask:0xf
	v_mov_b32_dpp v26, v7 row_ror:8 row_mask:0xf bank_mask:0xf
	v_mov_b32_dpp v6, v2 row_ror:8 row_mask:0xf bank_mask:0xc
	v_mov_b32_dpp v7, v3 row_ror:8 row_mask:0xf bank_mask:0xc
	v_mov_b32_dpp v2, v25 quad_perm:[0,1,2,3] row_mask:0xf bank_mask:0x3
	v_mov_b32_dpp v3, v26 quad_perm:[0,1,2,3] row_mask:0xf bank_mask:0x3
	s_waitcnt vmcnt(8)
	v_pk_add_f32 v[140:141], v[140:141], v[196:197]
	v_pk_add_f32 v[142:143], v[142:143], v[198:199]
	v_pk_add_f32 v[132:133], v[132:133], v[200:201]
	v_pk_add_f32 v[134:135], v[134:135], v[202:203]
	v_pk_add_f32 v[136:137], v[136:137], v[204:205]
	v_pk_add_f32 v[138:139], v[138:139], v[206:207]
	v_pk_add_f32 v[128:129], v[128:129], v[208:209]
	v_pk_add_f32 v[130:131], v[130:131], v[210:211]
	global_store_dwordx4 v177, v[140:143], s[76:77]
	global_store_dwordx4 v177, v[132:135], s[76:77] offset:512
	global_store_dwordx4 v195, v[136:139], s[76:77]
	global_store_dwordx4 v195, v[128:131], s[76:77] offset:512
	global_load_dwordx4 v[196:199], v170, s[80:81]
	global_load_dwordx4 v[200:203], v170, s[80:81] offset:512
	global_load_dwordx4 v[204:207], v171, s[80:81]
	global_load_dwordx4 v[208:211], v171, s[80:81] offset:512
	v_add_u32_e32 v170, 0x50000, v170
	v_add_u32_e32 v171, 0x50000, v171
	v_mul_f32_e32 v27, v180, v140
	v_mul_f32_e32 v28, v181, v141
	v_cvt_pk_bf16_f32 v30, v27, v28
	v_mul_f32_e32 v27, v182, v142
	v_mul_f32_e32 v28, v183, v143
	v_cvt_pk_bf16_f32 v31, v27, v28
	global_store_dwordx2 v247, v[30:31], s[88:89]
	v_mul_f32_e32 v27, v166, v132
	v_mul_f32_e32 v28, v167, v133
	v_cvt_pk_bf16_f32 v48, v27, v28
	v_mul_f32_e32 v27, v168, v134
	v_mul_f32_e32 v28, v169, v135
	v_cvt_pk_bf16_f32 v49, v27, v28
	global_store_dwordx2 v247, v[48:49], s[88:89] offset:256
	v_mul_f32_e32 v27, v180, v136
	v_mul_f32_e32 v28, v181, v137
	v_cvt_pk_bf16_f32 v30, v27, v28
	v_mul_f32_e32 v27, v182, v138
	v_mul_f32_e32 v28, v183, v139
	v_cvt_pk_bf16_f32 v31, v27, v28
	global_store_dwordx2 v24, v[30:31], s[88:89]
	v_mul_f32_e32 v27, v166, v128
	v_mul_f32_e32 v28, v167, v129
	v_cvt_pk_bf16_f32 v48, v27, v28
	v_mul_f32_e32 v27, v168, v130
	v_mul_f32_e32 v28, v169, v131
	v_cvt_pk_bf16_f32 v49, v27, v28
	global_store_dwordx2 v24, v[48:49], s[88:89] offset:256
	v_mul_f32_e32 v50, v141, v141
	v_mul_f32_e32 v29, v143, v143
	v_fmac_f32_e32 v50, v140, v140
	v_fmac_f32_e32 v29, v142, v142
	v_add_f32_e32 v50, v50, v29
	v_mul_f32_e32 v51, v137, v137
	v_mul_f32_e32 v29, v139, v139
	v_fmac_f32_e32 v51, v136, v136
	v_fmac_f32_e32 v29, v138, v138
	v_add_f32_e32 v51, v51, v29
	v_mul_f32_e32 v52, v133, v133
	v_mul_f32_e32 v29, v135, v135
	v_fmac_f32_e32 v52, v132, v132
	v_fmac_f32_e32 v29, v134, v134
	v_add_f32_e32 v52, v52, v29
	v_mul_f32_e32 v53, v129, v129
	v_mul_f32_e32 v29, v131, v131
	v_fmac_f32_e32 v53, v128, v128
	v_fmac_f32_e32 v29, v130, v130
	v_add_f32_e32 v53, v53, v29
	v_add_f32_dpp v27, v50, v50 row_ror:8 row_mask:0xf bank_mask:0x3
	v_add_f32_dpp v28, v52, v52 row_ror:8 row_mask:0xf bank_mask:0x3
	v_add_f32_dpp v27, v51, v51 row_ror:8 row_mask:0xf bank_mask:0xc
	v_add_f32_dpp v28, v53, v53 row_ror:8 row_mask:0xf bank_mask:0xc
	v_add_f32_e32 v27, v27, v28
	ds_bpermute_b32 v29, v54, v27
	s_waitcnt lgkmcnt(0)
	v_add_f32_e32 v27, v27, v29
	ds_bpermute_b32 v29, v55, v27
	s_waitcnt lgkmcnt(0)
; __device__ __forceinline__ unsigned cvt_pk_bf16(float lo, float hi) { unsigned r; asm volatile("v_cvt_pk_bf16_f32 %0, %1, %2" : "=v"(r) : "v"(lo), "v"(hi)); return r; }
;     __device__ __forceinline__ void operator()(const f32x4 (&acc)[2][2][4][2], const Unit& u, int wr, int wc, int fr, int fq, LAS unsigned char* lds) const {
;     ...
; #pragma unroll
;         for (int ai = 0; ai < 2; ++ai)
; #pragma unroll
;             for (int m = 0; m < 4; ++m) { const size_t ro = (size_t)(row0 + ai * HALF + m * 16) * ldc + col0; float ssq = 0.f;
; #pragma unroll
;                 for (int bj = 0; bj < 2; ++bj) { const size_t o = ro + bj * HALF;
;                     const f32x4 r0 = *(const f32x4*)(res + o), r1 = *(const f32x4*)(res + o + 4);
;                     const f32x4 x0 = r0 + acc[ai][bj][m][0], x1 = r1 + acc[ai][bj][m][1];
;                     *(f32x4*)(O + o) = x0; *(f32x4*)(O + o + 4) = x1;
;                     u32x4 hb; hb.x = cvt_pk_bf16(x0[0] * gg[bj][0][0], x0[1] * gg[bj][0][1]); hb.y = cvt_pk_bf16(x0[2] * gg[bj][0][2], x0[3] * gg[bj][0][3]);
;                     hb.z = cvt_pk_bf16(x1[0] * gg[bj][1][0], x1[1] * gg[bj][1][1]); hb.w = cvt_pk_bf16(x1[2] * gg[bj][1][2], x1[3] * gg[bj][1][3]);
;                     *(u32x4*)(H + o) = hb;
;                     ssq += ((x0[0] * x0[0] + x0[1] * x0[1]) + (x0[2] * x0[2] + x0[3] * x0[3])) + ((x1[0] * x1[0] + x1[1] * x1[1]) + (x1[2] * x1[2] + x1[3] * x1[3])); }
;                 ssq += __shfl_xor(ssq, 16); ssq += __shfl_xor(ssq, 32);
;                 if (fq == 0) part[(ai * HALF + wr * 64 + m * 16 + fr) * 4 + wc] = ssq; }
	v_add_f32_e32 v27, v27, v29
	s_and_saveexec_b64 s[14:15], s[42:43]
	ds_write_b32 v176, v27
	s_or_b64 exec, exec, s[14:15]
	v_add_u32_e32 v177, 0x10000, v177
	v_add_u32_e32 v195, 0x10000, v195
	v_add_u32_e32 v247, 0x8000, v247
	v_add_u32_e32 v24, 0x8000, v24
	s_waitcnt vmcnt(16)
	v_pk_add_f32 v[124:125], v[124:125], v[212:213]
	v_pk_add_f32 v[126:127], v[126:127], v[214:215]
	v_pk_add_f32 v[116:117], v[116:117], v[216:217]
	v_pk_add_f32 v[118:119], v[118:119], v[218:219]
	v_pk_add_f32 v[120:121], v[120:121], v[220:221]
	v_pk_add_f32 v[122:123], v[122:123], v[222:223]
	v_pk_add_f32 v[112:113], v[112:113], v[224:225]
	v_pk_add_f32 v[114:115], v[114:115], v[226:227]
	global_store_dwordx4 v177, v[124:127], s[76:77]
	global_store_dwordx4 v177, v[116:119], s[76:77] offset:512
	global_store_dwordx4 v195, v[120:123], s[76:77]
	global_store_dwordx4 v195, v[112:115], s[76:77] offset:512
	global_load_dwordx4 v[212:215], v170, s[80:81]
	global_load_dwordx4 v[216:219], v170, s[80:81] offset:512
	global_load_dwordx4 v[220:223], v171, s[80:81]
	global_load_dwordx4 v[224:227], v171, s[80:81] offset:512
	v_add_u32_e32 v170, 0x10000, v170
	v_add_u32_e32 v171, 0x10000, v171
	v_mul_f32_e32 v27, v180, v124
	v_mul_f32_e32 v28, v181, v125
	v_cvt_pk_bf16_f32 v30, v27, v28
	v_mul_f32_e32 v27, v182, v126
	v_mul_f32_e32 v28, v183, v127
	v_cvt_pk_bf16_f32 v31, v27, v28
	global_store_dwordx2 v247, v[30:31], s[88:89]
	v_mul_f32_e32 v27, v166, v116
	v_mul_f32_e32 v28, v167, v117
	v_cvt_pk_bf16_f32 v48, v27, v28
	v_mul_f32_e32 v27, v168, v118
	v_mul_f32_e32 v28, v169, v119
	v_cvt_pk_bf16_f32 v49, v27, v28
	global_store_dwordx2 v247, v[48:49], s[88:89] offset:256
	v_mul_f32_e32 v27, v180, v120
	v_mul_f32_e32 v28, v181, v121
	v_cvt_pk_bf16_f32 v30, v27, v28
	v_mul_f32_e32 v27, v182, v122
	v_mul_f32_e32 v28, v183, v123
	v_cvt_pk_bf16_f32 v31, v27, v28
	global_store_dwordx2 v24, v[30:31], s[88:89]
	v_mul_f32_e32 v27, v166, v112
	v_mul_f32_e32 v28, v167, v113
	v_cvt_pk_bf16_f32 v48, v27, v28
	v_mul_f32_e32 v27, v168, v114
	v_mul_f32_e32 v28, v169, v115
	v_cvt_pk_bf16_f32 v49, v27, v28
	global_store_dwordx2 v24, v[48:49], s[88:89] offset:256
	v_mul_f32_e32 v50, v125, v125
	v_mul_f32_e32 v29, v127, v127
	v_fmac_f32_e32 v50, v124, v124
	v_fmac_f32_e32 v29, v126, v126
	v_add_f32_e32 v50, v50, v29
	v_mul_f32_e32 v51, v121, v121
	v_mul_f32_e32 v29, v123, v123
	v_fmac_f32_e32 v51, v120, v120
	v_fmac_f32_e32 v29, v122, v122
	v_add_f32_e32 v51, v51, v29
	v_mul_f32_e32 v52, v117, v117
	v_mul_f32_e32 v29, v119, v119
	v_fmac_f32_e32 v52, v116, v116
	v_fmac_f32_e32 v29, v118, v118
	v_add_f32_e32 v52, v52, v29
	v_mul_f32_e32 v53, v113, v113
	v_mul_f32_e32 v29, v115, v115
	v_fmac_f32_e32 v53, v112, v112
	v_fmac_f32_e32 v29, v114, v114
	v_add_f32_e32 v53, v53, v29
	v_add_f32_dpp v27, v50, v50 row_ror:8 row_mask:0xf bank_mask:0x3
	v_add_f32_dpp v28, v52, v52 row_ror:8 row_mask:0xf bank_mask:0x3
	v_add_f32_dpp v27, v51, v51 row_ror:8 row_mask:0xf bank_mask:0xc
	v_add_f32_dpp v28, v53, v53 row_ror:8 row_mask:0xf bank_mask:0xc
	v_add_f32_e32 v27, v27, v28
	ds_bpermute_b32 v29, v54, v27
	s_waitcnt lgkmcnt(0)
	v_add_f32_e32 v27, v27, v29
	ds_bpermute_b32 v29, v55, v27
	s_waitcnt lgkmcnt(0)
	v_add_f32_e32 v27, v27, v29
	s_and_saveexec_b64 s[14:15], s[42:43]
	ds_write_b32 v176, v27 offset:256
	s_or_b64 exec, exec, s[14:15]
	v_add_u32_e32 v177, 0x10000, v177
	v_add_u32_e32 v195, 0x10000, v195
	v_add_u32_e32 v247, 0x8000, v247
	v_add_u32_e32 v24, 0x8000, v24
	s_waitcnt vmcnt(24)
	v_pk_add_f32 v[108:109], v[108:109], v[228:229]
	v_pk_add_f32 v[110:111], v[110:111], v[230:231]
	v_pk_add_f32 v[100:101], v[100:101], v[232:233]
	v_pk_add_f32 v[102:103], v[102:103], v[234:235]
	v_pk_add_f32 v[104:105], v[104:105], v[236:237]
	v_pk_add_f32 v[106:107], v[106:107], v[238:239]
	v_pk_add_f32 v[96:97], v[96:97], v[240:241]
	v_pk_add_f32 v[98:99], v[98:99], v[242:243]
	global_store_dwordx4 v177, v[108:111], s[76:77]
	global_store_dwordx4 v177, v[100:103], s[76:77] offset:512
	global_store_dwordx4 v195, v[104:107], s[76:77]
	global_store_dwordx4 v195, v[96:99], s[76:77] offset:512
	global_load_dwordx4 v[228:231], v170, s[80:81]
	global_load_dwordx4 v[232:235], v170, s[80:81] offset:512
	global_load_dwordx4 v[236:239], v171, s[80:81]
	global_load_dwordx4 v[240:243], v171, s[80:81] offset:512
	v_add_u32_e32 v170, 0x10000, v170
	v_add_u32_e32 v171, 0x10000, v171
	v_mul_f32_e32 v27, v180, v108
	v_mul_f32_e32 v28, v181, v109
	v_cvt_pk_bf16_f32 v30, v27, v28
	v_mul_f32_e32 v27, v182, v110
	v_mul_f32_e32 v28, v183, v111
	v_cvt_pk_bf16_f32 v31, v27, v28
	global_store_dwordx2 v247, v[30:31], s[88:89]
	v_mul_f32_e32 v27, v166, v100
	v_mul_f32_e32 v28, v167, v101
	v_cvt_pk_bf16_f32 v48, v27, v28
	v_mul_f32_e32 v27, v168, v102
	v_mul_f32_e32 v28, v169, v103
	v_cvt_pk_bf16_f32 v49, v27, v28
	global_store_dwordx2 v247, v[48:49], s[88:89] offset:256
	v_mul_f32_e32 v27, v180, v104
	v_mul_f32_e32 v28, v181, v105
	v_cvt_pk_bf16_f32 v30, v27, v28
	v_mul_f32_e32 v27, v182, v106
	v_mul_f32_e32 v28, v183, v107
	v_cvt_pk_bf16_f32 v31, v27, v28
	global_store_dwordx2 v24, v[30:31], s[88:89]
	v_mul_f32_e32 v27, v166, v96
	v_mul_f32_e32 v28, v167, v97
	v_cvt_pk_bf16_f32 v48, v27, v28
	v_mul_f32_e32 v27, v168, v98
	v_mul_f32_e32 v28, v169, v99
	v_cvt_pk_bf16_f32 v49, v27, v28
	global_store_dwordx2 v24, v[48:49], s[88:89] offset:256
	v_mul_f32_e32 v50, v109, v109
	v_mul_f32_e32 v29, v111, v111
	v_fmac_f32_e32 v50, v108, v108
	v_fmac_f32_e32 v29, v110, v110
	v_add_f32_e32 v50, v50, v29
	v_mul_f32_e32 v51, v105, v105
	v_mul_f32_e32 v29, v107, v107
	v_fmac_f32_e32 v51, v104, v104
	v_fmac_f32_e32 v29, v106, v106
	v_add_f32_e32 v51, v51, v29
	v_mul_f32_e32 v52, v101, v101
	v_mul_f32_e32 v29, v103, v103
	v_fmac_f32_e32 v52, v100, v100
	v_fmac_f32_e32 v29, v102, v102
	v_add_f32_e32 v52, v52, v29
	v_mul_f32_e32 v53, v97, v97
	v_mul_f32_e32 v29, v99, v99
	v_fmac_f32_e32 v53, v96, v96
	v_fmac_f32_e32 v29, v98, v98
	v_add_f32_e32 v53, v53, v29
	v_add_f32_dpp v27, v50, v50 row_ror:8 row_mask:0xf bank_mask:0x3
	v_add_f32_dpp v28, v52, v52 row_ror:8 row_mask:0xf bank_mask:0x3
	v_add_f32_dpp v27, v51, v51 row_ror:8 row_mask:0xf bank_mask:0xc
	v_add_f32_dpp v28, v53, v53 row_ror:8 row_mask:0xf bank_mask:0xc
	v_add_f32_e32 v27, v27, v28
	ds_bpermute_b32 v29, v54, v27
	s_waitcnt lgkmcnt(0)
; __device__ __forceinline__ unsigned cvt_pk_bf16(float lo, float hi) { unsigned r; asm volatile("v_cvt_pk_bf16_f32 %0, %1, %2" : "=v"(r) : "v"(lo), "v"(hi)); return r; }
;     __device__ __forceinline__ void operator()(const f32x4 (&acc)[2][2][4][2], const Unit& u, int wr, int wc, int fr, int fq, LAS unsigned char* lds) const {
;     ...
; #pragma unroll
;         for (int ai = 0; ai < 2; ++ai)
; #pragma unroll
;             for (int m = 0; m < 4; ++m) { const size_t ro = (size_t)(row0 + ai * HALF + m * 16) * ldc + col0; float ssq = 0.f;
; #pragma unroll
;                 for (int bj = 0; bj < 2; ++bj) { const size_t o = ro + bj * HALF;
;                     const f32x4 r0 = *(const f32x4*)(res + o), r1 = *(const f32x4*)(res + o + 4);
;                     const f32x4 x0 = r0 + acc[ai][bj][m][0], x1 = r1 + acc[ai][bj][m][1];
;                     *(f32x4*)(O + o) = x0; *(f32x4*)(O + o + 4) = x1;
;                     u32x4 hb; hb.x = cvt_pk_bf16(x0[0] * gg[bj][0][0], x0[1] * gg[bj][0][1]); hb.y = cvt_pk_bf16(x0[2] * gg[bj][0][2], x0[3] * gg[bj][0][3]);
;                     hb.z = cvt_pk_bf16(x1[0] * gg[bj][1][0], x1[1] * gg[bj][1][1]); hb.w = cvt_pk_bf16(x1[2] * gg[bj][1][2], x1[3] * gg[bj][1][3]);
;                     *(u32x4*)(H + o) = hb;
;                     ssq += ((x0[0] * x0[0] + x0[1] * x0[1]) + (x0[2] * x0[2] + x0[3] * x0[3])) + ((x1[0] * x1[0] + x1[1] * x1[1]) + (x1[2] * x1[2] + x1[3] * x1[3])); }
;                 ssq += __shfl_xor(ssq, 16); ssq += __shfl_xor(ssq, 32);
;                 if (fq == 0) part[(ai * HALF + wr * 64 + m * 16 + fr) * 4 + wc] = ssq; }
	v_add_f32_e32 v27, v27, v29
	ds_bpermute_b32 v29, v55, v27
	s_waitcnt lgkmcnt(0)
	v_add_f32_e32 v27, v27, v29
	s_and_saveexec_b64 s[14:15], s[42:43]
	ds_write_b32 v176, v27 offset:512
	s_or_b64 exec, exec, s[14:15]
	v_add_u32_e32 v177, 0x10000, v177
	v_add_u32_e32 v195, 0x10000, v195
	v_add_u32_e32 v247, 0x8000, v247
	v_add_u32_e32 v24, 0x8000, v24
	s_waitcnt vmcnt(28)
	v_pk_add_f32 v[92:93], v[92:93], v[196:197]
	v_pk_add_f32 v[94:95], v[94:95], v[198:199]
	v_pk_add_f32 v[84:85], v[84:85], v[200:201]
	v_pk_add_f32 v[86:87], v[86:87], v[202:203]
	v_pk_add_f32 v[88:89], v[88:89], v[204:205]
	v_pk_add_f32 v[90:91], v[90:91], v[206:207]
	v_pk_add_f32 v[80:81], v[80:81], v[208:209]
	v_pk_add_f32 v[82:83], v[82:83], v[210:211]
	global_store_dwordx4 v177, v[92:95], s[76:77]
	global_store_dwordx4 v177, v[84:87], s[76:77] offset:512
	global_store_dwordx4 v195, v[88:91], s[76:77]
	global_store_dwordx4 v195, v[80:83], s[76:77] offset:512
	global_load_dwordx4 v[196:199], v170, s[80:81]
	global_load_dwordx4 v[200:203], v170, s[80:81] offset:512
	global_load_dwordx4 v[204:207], v171, s[80:81]
	global_load_dwordx4 v[208:211], v171, s[80:81] offset:512
	v_add_u32_e32 v170, 0x10000, v170
	v_add_u32_e32 v171, 0x10000, v171
	v_mul_f32_e32 v27, v180, v92
	v_mul_f32_e32 v28, v181, v93
	v_cvt_pk_bf16_f32 v30, v27, v28
	v_mul_f32_e32 v27, v182, v94
	v_mul_f32_e32 v28, v183, v95
	v_cvt_pk_bf16_f32 v31, v27, v28
	global_store_dwordx2 v247, v[30:31], s[88:89]
	v_mul_f32_e32 v27, v166, v84
	v_mul_f32_e32 v28, v167, v85
	v_cvt_pk_bf16_f32 v48, v27, v28
	v_mul_f32_e32 v27, v168, v86
	v_mul_f32_e32 v28, v169, v87
	v_cvt_pk_bf16_f32 v49, v27, v28
	global_store_dwordx2 v247, v[48:49], s[88:89] offset:256
	v_mul_f32_e32 v27, v180, v88
	v_mul_f32_e32 v28, v181, v89
	v_cvt_pk_bf16_f32 v30, v27, v28
	v_mul_f32_e32 v27, v182, v90
	v_mul_f32_e32 v28, v183, v91
	v_cvt_pk_bf16_f32 v31, v27, v28
	global_store_dwordx2 v24, v[30:31], s[88:89]
	v_mul_f32_e32 v27, v166, v80
	v_mul_f32_e32 v28, v167, v81
	v_cvt_pk_bf16_f32 v48, v27, v28
	v_mul_f32_e32 v27, v168, v82
	v_mul_f32_e32 v28, v169, v83
	v_cvt_pk_bf16_f32 v49, v27, v28
	global_store_dwordx2 v24, v[48:49], s[88:89] offset:256
	v_mul_f32_e32 v50, v93, v93
	v_mul_f32_e32 v29, v95, v95
	v_fmac_f32_e32 v50, v92, v92
	v_fmac_f32_e32 v29, v94, v94
	v_add_f32_e32 v50, v50, v29
	v_mul_f32_e32 v51, v89, v89
	v_mul_f32_e32 v29, v91, v91
	v_fmac_f32_e32 v51, v88, v88
	v_fmac_f32_e32 v29, v90, v90
	v_add_f32_e32 v51, v51, v29
	v_mul_f32_e32 v52, v85, v85
	v_mul_f32_e32 v29, v87, v87
	v_fmac_f32_e32 v52, v84, v84
	v_fmac_f32_e32 v29, v86, v86
	v_add_f32_e32 v52, v52, v29
	v_mul_f32_e32 v53, v81, v81
	v_mul_f32_e32 v29, v83, v83
	v_fmac_f32_e32 v53, v80, v80
	v_fmac_f32_e32 v29, v82, v82
	v_add_f32_e32 v53, v53, v29
	v_add_f32_dpp v27, v50, v50 row_ror:8 row_mask:0xf bank_mask:0x3
	v_add_f32_dpp v28, v52, v52 row_ror:8 row_mask:0xf bank_mask:0x3
	v_add_f32_dpp v27, v51, v51 row_ror:8 row_mask:0xf bank_mask:0xc
	v_add_f32_dpp v28, v53, v53 row_ror:8 row_mask:0xf bank_mask:0xc
	v_add_f32_e32 v27, v27, v28
	ds_bpermute_b32 v29, v54, v27
	s_waitcnt lgkmcnt(0)
	v_add_f32_e32 v27, v27, v29
	ds_bpermute_b32 v29, v55, v27
	s_waitcnt lgkmcnt(0)
	v_add_f32_e32 v27, v27, v29
	s_and_saveexec_b64 s[14:15], s[42:43]
	ds_write_b32 v176, v27 offset:768
	s_or_b64 exec, exec, s[14:15]
	v_add_u32_e32 v177, 0x50000, v177
	v_add_u32_e32 v195, 0x50000, v195
	v_add_u32_e32 v247, 0x28000, v247
	v_add_u32_e32 v24, 0x28000, v24
	s_waitcnt vmcnt(28)
	v_pk_add_f32 v[76:77], v[76:77], v[212:213]
	v_pk_add_f32 v[78:79], v[78:79], v[214:215]
	v_pk_add_f32 v[68:69], v[68:69], v[216:217]
	v_pk_add_f32 v[70:71], v[70:71], v[218:219]
	v_pk_add_f32 v[72:73], v[72:73], v[220:221]
	v_pk_add_f32 v[74:75], v[74:75], v[222:223]
	v_pk_add_f32 v[64:65], v[64:65], v[224:225]
	v_pk_add_f32 v[66:67], v[66:67], v[226:227]
	global_store_dwordx4 v177, v[76:79], s[76:77]
	global_store_dwordx4 v177, v[68:71], s[76:77] offset:512
	global_store_dwordx4 v195, v[72:75], s[76:77]
	global_store_dwordx4 v195, v[64:67], s[76:77] offset:512
	global_load_dwordx4 v[212:215], v170, s[80:81]
	global_load_dwordx4 v[216:219], v170, s[80:81] offset:512
	global_load_dwordx4 v[220:223], v171, s[80:81]
	global_load_dwordx4 v[224:227], v171, s[80:81] offset:512
	v_mul_f32_e32 v27, v180, v76
	v_mul_f32_e32 v28, v181, v77
	v_cvt_pk_bf16_f32 v30, v27, v28
	v_mul_f32_e32 v27, v182, v78
	v_mul_f32_e32 v28, v183, v79
	v_cvt_pk_bf16_f32 v31, v27, v28
	global_store_dwordx2 v247, v[30:31], s[88:89]
	v_mul_f32_e32 v27, v166, v68
	v_mul_f32_e32 v28, v167, v69
	v_cvt_pk_bf16_f32 v48, v27, v28
	v_mul_f32_e32 v27, v168, v70
	v_mul_f32_e32 v28, v169, v71
	v_cvt_pk_bf16_f32 v49, v27, v28
	global_store_dwordx2 v247, v[48:49], s[88:89] offset:256
	v_mul_f32_e32 v27, v180, v72
	v_mul_f32_e32 v28, v181, v73
	v_cvt_pk_bf16_f32 v30, v27, v28
	v_mul_f32_e32 v27, v182, v74
	v_mul_f32_e32 v28, v183, v75
	v_cvt_pk_bf16_f32 v31, v27, v28
	global_store_dwordx2 v24, v[30:31], s[88:89]
	v_mul_f32_e32 v27, v166, v64
	v_mul_f32_e32 v28, v167, v65
	v_cvt_pk_bf16_f32 v48, v27, v28
	v_mul_f32_e32 v27, v168, v66
	v_mul_f32_e32 v28, v169, v67
	v_cvt_pk_bf16_f32 v49, v27, v28
	global_store_dwordx2 v24, v[48:49], s[88:89] offset:256
	v_mul_f32_e32 v50, v77, v77
	v_mul_f32_e32 v29, v79, v79
	v_fmac_f32_e32 v50, v76, v76
	v_fmac_f32_e32 v29, v78, v78
	v_add_f32_e32 v50, v50, v29
	v_mul_f32_e32 v51, v73, v73
	v_mul_f32_e32 v29, v75, v75
	v_fmac_f32_e32 v51, v72, v72
	v_fmac_f32_e32 v29, v74, v74
	v_add_f32_e32 v51, v51, v29
	v_mul_f32_e32 v52, v69, v69
	v_mul_f32_e32 v29, v71, v71
	v_fmac_f32_e32 v52, v68, v68
	v_fmac_f32_e32 v29, v70, v70
	v_add_f32_e32 v52, v52, v29
	v_mul_f32_e32 v53, v65, v65
	v_mul_f32_e32 v29, v67, v67
	v_fmac_f32_e32 v53, v64, v64
	v_fmac_f32_e32 v29, v66, v66
	v_add_f32_e32 v53, v53, v29
	v_add_f32_dpp v27, v50, v50 row_ror:8 row_mask:0xf bank_mask:0x3
	v_add_f32_dpp v28, v52, v52 row_ror:8 row_mask:0xf bank_mask:0x3
	v_add_f32_dpp v27, v51, v51 row_ror:8 row_mask:0xf bank_mask:0xc
	v_add_f32_dpp v28, v53, v53 row_ror:8 row_mask:0xf bank_mask:0xc
	v_add_f32_e32 v27, v27, v28
	ds_bpermute_b32 v29, v54, v27
	s_waitcnt lgkmcnt(0)
; __device__ __forceinline__ unsigned cvt_pk_bf16(float lo, float hi) { unsigned r; asm volatile("v_cvt_pk_bf16_f32 %0, %1, %2" : "=v"(r) : "v"(lo), "v"(hi)); return r; }
;     __device__ __forceinline__ void operator()(const f32x4 (&acc)[2][2][4][2], const Unit& u, int wr, int wc, int fr, int fq, LAS unsigned char* lds) const {
;     ...
; #pragma unroll
;         for (int ai = 0; ai < 2; ++ai)
; #pragma unroll
;             for (int m = 0; m < 4; ++m) { const size_t ro = (size_t)(row0 + ai * HALF + m * 16) * ldc + col0; float ssq = 0.f;
; #pragma unroll
;                 for (int bj = 0; bj < 2; ++bj) { const size_t o = ro + bj * HALF;
;                     const f32x4 r0 = *(const f32x4*)(res + o), r1 = *(const f32x4*)(res + o + 4);
;                     const f32x4 x0 = r0 + acc[ai][bj][m][0], x1 = r1 + acc[ai][bj][m][1];
;                     *(f32x4*)(O + o) = x0; *(f32x4*)(O + o + 4) = x1;
;                     u32x4 hb; hb.x = cvt_pk_bf16(x0[0] * gg[bj][0][0], x0[1] * gg[bj][0][1]); hb.y = cvt_pk_bf16(x0[2] * gg[bj][0][2], x0[3] * gg[bj][0][3]);
;                     hb.z = cvt_pk_bf16(x1[0] * gg[bj][1][0], x1[1] * gg[bj][1][1]); hb.w = cvt_pk_bf16(x1[2] * gg[bj][1][2], x1[3] * gg[bj][1][3]);
;                     *(u32x4*)(H + o) = hb;
;                     ssq += ((x0[0] * x0[0] + x0[1] * x0[1]) + (x0[2] * x0[2] + x0[3] * x0[3])) + ((x1[0] * x1[0] + x1[1] * x1[1]) + (x1[2] * x1[2] + x1[3] * x1[3])); }
;                 ssq += __shfl_xor(ssq, 16); ssq += __shfl_xor(ssq, 32);
;                 if (fq == 0) part[(ai * HALF + wr * 64 + m * 16 + fr) * 4 + wc] = ssq; }
	v_add_f32_e32 v27, v27, v29
	ds_bpermute_b32 v29, v55, v27
	s_waitcnt lgkmcnt(0)
	v_add_f32_e32 v27, v27, v29
	s_and_saveexec_b64 s[14:15], s[42:43]
	ds_write_b32 v176, v27 offset:2048
	s_or_b64 exec, exec, s[14:15]
	v_add_u32_e32 v177, 0x10000, v177
	v_add_u32_e32 v195, 0x10000, v195
	v_add_u32_e32 v247, 0x8000, v247
	v_add_u32_e32 v24, 0x8000, v24
	s_waitcnt vmcnt(28)
	v_pk_add_f32 v[60:61], v[60:61], v[228:229]
	v_pk_add_f32 v[62:63], v[62:63], v[230:231]
	v_pk_add_f32 v[44:45], v[44:45], v[232:233]
	v_pk_add_f32 v[46:47], v[46:47], v[234:235]
	v_pk_add_f32 v[56:57], v[56:57], v[236:237]
	v_pk_add_f32 v[58:59], v[58:59], v[238:239]
	v_pk_add_f32 v[40:41], v[40:41], v[240:241]
	v_pk_add_f32 v[42:43], v[42:43], v[242:243]
	global_store_dwordx4 v177, v[60:63], s[76:77]
	global_store_dwordx4 v177, v[44:47], s[76:77] offset:512
	global_store_dwordx4 v195, v[56:59], s[76:77]
	global_store_dwordx4 v195, v[40:43], s[76:77] offset:512
	v_mul_f32_e32 v27, v180, v60
	v_mul_f32_e32 v28, v181, v61
	v_cvt_pk_bf16_f32 v30, v27, v28
	v_mul_f32_e32 v27, v182, v62
	v_mul_f32_e32 v28, v183, v63
	v_cvt_pk_bf16_f32 v31, v27, v28
	global_store_dwordx2 v247, v[30:31], s[88:89]
	v_mul_f32_e32 v27, v166, v44
	v_mul_f32_e32 v28, v167, v45
	v_cvt_pk_bf16_f32 v48, v27, v28
	v_mul_f32_e32 v27, v168, v46
	v_mul_f32_e32 v28, v169, v47
	v_cvt_pk_bf16_f32 v49, v27, v28
	global_store_dwordx2 v247, v[48:49], s[88:89] offset:256
	v_mul_f32_e32 v27, v180, v56
	v_mul_f32_e32 v28, v181, v57
	v_cvt_pk_bf16_f32 v30, v27, v28
	v_mul_f32_e32 v27, v182, v58
	v_mul_f32_e32 v28, v183, v59
	v_cvt_pk_bf16_f32 v31, v27, v28
	global_store_dwordx2 v24, v[30:31], s[88:89]
	v_mul_f32_e32 v27, v166, v40
	v_mul_f32_e32 v28, v167, v41
	v_cvt_pk_bf16_f32 v48, v27, v28
	v_mul_f32_e32 v27, v168, v42
	v_mul_f32_e32 v28, v169, v43
	v_cvt_pk_bf16_f32 v49, v27, v28
	global_store_dwordx2 v24, v[48:49], s[88:89] offset:256
	v_mul_f32_e32 v50, v61, v61
	v_mul_f32_e32 v29, v63, v63
	v_fmac_f32_e32 v50, v60, v60
	v_fmac_f32_e32 v29, v62, v62
	v_add_f32_e32 v50, v50, v29
	v_mul_f32_e32 v51, v57, v57
	v_mul_f32_e32 v29, v59, v59
	v_fmac_f32_e32 v51, v56, v56
	v_fmac_f32_e32 v29, v58, v58
	v_add_f32_e32 v51, v51, v29
	v_mul_f32_e32 v52, v45, v45
	v_mul_f32_e32 v29, v47, v47
	v_fmac_f32_e32 v52, v44, v44
	v_fmac_f32_e32 v29, v46, v46
	v_add_f32_e32 v52, v52, v29
	v_mul_f32_e32 v53, v41, v41
	v_mul_f32_e32 v29, v43, v43
	v_fmac_f32_e32 v53, v40, v40
	v_fmac_f32_e32 v29, v42, v42
	v_add_f32_e32 v53, v53, v29
	v_add_f32_dpp v27, v50, v50 row_ror:8 row_mask:0xf bank_mask:0x3
	v_add_f32_dpp v28, v52, v52 row_ror:8 row_mask:0xf bank_mask:0x3
	v_add_f32_dpp v27, v51, v51 row_ror:8 row_mask:0xf bank_mask:0xc
	v_add_f32_dpp v28, v53, v53 row_ror:8 row_mask:0xf bank_mask:0xc
	v_add_f32_e32 v27, v27, v28
	ds_bpermute_b32 v29, v54, v27
	s_waitcnt lgkmcnt(0)
	v_add_f32_e32 v27, v27, v29
	ds_bpermute_b32 v29, v55, v27
	s_waitcnt lgkmcnt(0)
	v_add_f32_e32 v27, v27, v29
	s_and_saveexec_b64 s[14:15], s[42:43]
	ds_write_b32 v176, v27 offset:2304
	s_or_b64 exec, exec, s[14:15]
	v_add_u32_e32 v177, 0x10000, v177
	v_add_u32_e32 v195, 0x10000, v195
	v_add_u32_e32 v247, 0x8000, v247
	v_add_u32_e32 v24, 0x8000, v24
	s_waitcnt vmcnt(24)
	v_pk_add_f32 v[36:37], v[36:37], v[196:197]
	v_pk_add_f32 v[38:39], v[38:39], v[198:199]
	v_pk_add_f32 v[20:21], v[20:21], v[200:201]
	v_pk_add_f32 v[22:23], v[22:23], v[202:203]
	v_pk_add_f32 v[32:33], v[32:33], v[204:205]
	v_pk_add_f32 v[34:35], v[34:35], v[206:207]
	v_pk_add_f32 v[16:17], v[16:17], v[208:209]
	v_pk_add_f32 v[18:19], v[18:19], v[210:211]
	global_store_dwordx4 v177, v[36:39], s[76:77]
	global_store_dwordx4 v177, v[20:23], s[76:77] offset:512
	global_store_dwordx4 v195, v[32:35], s[76:77]
	global_store_dwordx4 v195, v[16:19], s[76:77] offset:512
	v_mul_f32_e32 v27, v180, v36
	v_mul_f32_e32 v28, v181, v37
	v_cvt_pk_bf16_f32 v30, v27, v28
	v_mul_f32_e32 v27, v182, v38
	v_mul_f32_e32 v28, v183, v39
	v_cvt_pk_bf16_f32 v31, v27, v28
	global_store_dwordx2 v247, v[30:31], s[88:89]
	v_mul_f32_e32 v27, v166, v20
	v_mul_f32_e32 v28, v167, v21
	v_cvt_pk_bf16_f32 v48, v27, v28
	v_mul_f32_e32 v27, v168, v22
	v_mul_f32_e32 v28, v169, v23
	v_cvt_pk_bf16_f32 v49, v27, v28
	global_store_dwordx2 v247, v[48:49], s[88:89] offset:256
	v_mul_f32_e32 v27, v180, v32
	v_mul_f32_e32 v28, v181, v33
	v_cvt_pk_bf16_f32 v30, v27, v28
	v_mul_f32_e32 v27, v182, v34
	v_mul_f32_e32 v28, v183, v35
	v_cvt_pk_bf16_f32 v31, v27, v28
	global_store_dwordx2 v24, v[30:31], s[88:89]
	v_mul_f32_e32 v27, v166, v16
	v_mul_f32_e32 v28, v167, v17
	v_cvt_pk_bf16_f32 v48, v27, v28
	v_mul_f32_e32 v27, v168, v18
	v_mul_f32_e32 v28, v169, v19
	v_cvt_pk_bf16_f32 v49, v27, v28
	global_store_dwordx2 v24, v[48:49], s[88:89] offset:256
	v_mul_f32_e32 v50, v37, v37
	v_mul_f32_e32 v29, v39, v39
	v_fmac_f32_e32 v50, v36, v36
	v_fmac_f32_e32 v29, v38, v38
	v_add_f32_e32 v50, v50, v29
	v_mul_f32_e32 v51, v33, v33
	v_mul_f32_e32 v29, v35, v35
	v_fmac_f32_e32 v51, v32, v32
	v_fmac_f32_e32 v29, v34, v34
	v_add_f32_e32 v51, v51, v29
	v_mul_f32_e32 v52, v21, v21
	v_mul_f32_e32 v29, v23, v23
	v_fmac_f32_e32 v52, v20, v20
	v_fmac_f32_e32 v29, v22, v22
	v_add_f32_e32 v52, v52, v29
	v_mul_f32_e32 v53, v17, v17
	v_mul_f32_e32 v29, v19, v19
	v_fmac_f32_e32 v53, v16, v16
	v_fmac_f32_e32 v29, v18, v18
	v_add_f32_e32 v53, v53, v29
	v_add_f32_dpp v27, v50, v50 row_ror:8 row_mask:0xf bank_mask:0x3
	v_add_f32_dpp v28, v52, v52 row_ror:8 row_mask:0xf bank_mask:0x3
	v_add_f32_dpp v27, v51, v51 row_ror:8 row_mask:0xf bank_mask:0xc
	v_add_f32_dpp v28, v53, v53 row_ror:8 row_mask:0xf bank_mask:0xc
	v_add_f32_e32 v27, v27, v28
	ds_bpermute_b32 v29, v54, v27
	s_waitcnt lgkmcnt(0)
; #define LAS __attribute__((address_space(3)))
; __device__ __forceinline__ unsigned cvt_pk_bf16(float lo, float hi) { unsigned r; asm volatile("v_cvt_pk_bf16_f32 %0, %1, %2" : "=v"(r) : "v"(lo), "v"(hi)); return r; }
;     __device__ __forceinline__ void operator()(const f32x4 (&acc)[2][2][4][2], const Unit& u, int wr, int wc, int fr, int fq, LAS unsigned char* lds) const {
;     ...
; #pragma unroll
;         for (int ai = 0; ai < 2; ++ai)
; #pragma unroll
;             for (int m = 0; m < 4; ++m) { const size_t ro = (size_t)(row0 + ai * HALF + m * 16) * ldc + col0; float ssq = 0.f;
; #pragma unroll
;                 for (int bj = 0; bj < 2; ++bj) { const size_t o = ro + bj * HALF;
;                     const f32x4 r0 = *(const f32x4*)(res + o), r1 = *(const f32x4*)(res + o + 4);
;                     const f32x4 x0 = r0 + acc[ai][bj][m][0], x1 = r1 + acc[ai][bj][m][1];
;                     *(f32x4*)(O + o) = x0; *(f32x4*)(O + o + 4) = x1;
;                     u32x4 hb; hb.x = cvt_pk_bf16(x0[0] * gg[bj][0][0], x0[1] * gg[bj][0][1]); hb.y = cvt_pk_bf16(x0[2] * gg[bj][0][2], x0[3] * gg[bj][0][3]);
;                     hb.z = cvt_pk_bf16(x1[0] * gg[bj][1][0], x1[1] * gg[bj][1][1]); hb.w = cvt_pk_bf16(x1[2] * gg[bj][1][2], x1[3] * gg[bj][1][3]);
;                     *(u32x4*)(H + o) = hb;
;                     ssq += ((x0[0] * x0[0] + x0[1] * x0[1]) + (x0[2] * x0[2] + x0[3] * x0[3])) + ((x1[0] * x1[0] + x1[1] * x1[1]) + (x1[2] * x1[2] + x1[3] * x1[3])); }
;                 ssq += __shfl_xor(ssq, 16); ssq += __shfl_xor(ssq, 32);
;                 if (fq == 0) part[(ai * HALF + wr * 64 + m * 16 + fr) * 4 + wc] = ssq; }
;         asm volatile("s_waitcnt lgkmcnt(0)" ::: "memory"); __builtin_amdgcn_s_barrier(); asm volatile("" ::: "memory");
;         const int t = threadIdx.x;
;         if (t < 256) { const f32x4 p = *(const LAS f32x4*)(part + t * 4); rss[(size_t)u.pn * NTOK + u.pm * BM + t] = (p[0] + p[1]) + (p[2] + p[3]); }
	v_add_f32_e32 v27, v27, v29
	ds_bpermute_b32 v29, v55, v27
	s_waitcnt lgkmcnt(0)
	v_add_f32_e32 v27, v27, v29
	s_and_saveexec_b64 s[14:15], s[42:43]
	ds_write_b32 v176, v27 offset:2560
	s_or_b64 exec, exec, s[14:15]
	v_add_u32_e32 v177, 0x10000, v177
	v_add_u32_e32 v195, 0x10000, v195
	v_add_u32_e32 v247, 0x8000, v247
	v_add_u32_e32 v24, 0x8000, v24
	s_waitcnt vmcnt(20)
	v_pk_add_f32 v[12:13], v[12:13], v[212:213]
	v_pk_add_f32 v[14:15], v[14:15], v[214:215]
	v_pk_add_f32 v[4:5], v[4:5], v[216:217]
	v_pk_add_f32 v[6:7], v[6:7], v[218:219]
	v_pk_add_f32 v[8:9], v[8:9], v[220:221]
	v_pk_add_f32 v[10:11], v[10:11], v[222:223]
	v_pk_add_f32 v[0:1], v[0:1], v[224:225]
	v_pk_add_f32 v[2:3], v[2:3], v[226:227]
	global_store_dwordx4 v177, v[12:15], s[76:77]
	global_store_dwordx4 v177, v[4:7], s[76:77] offset:512
	global_store_dwordx4 v195, v[8:11], s[76:77]
	global_store_dwordx4 v195, v[0:3], s[76:77] offset:512
	v_mul_f32_e32 v27, v180, v12
	v_mul_f32_e32 v28, v181, v13
	v_cvt_pk_bf16_f32 v30, v27, v28
	v_mul_f32_e32 v27, v182, v14
	v_mul_f32_e32 v28, v183, v15
	v_cvt_pk_bf16_f32 v31, v27, v28
	global_store_dwordx2 v247, v[30:31], s[88:89]
	v_mul_f32_e32 v27, v166, v4
	v_mul_f32_e32 v28, v167, v5
	v_cvt_pk_bf16_f32 v48, v27, v28
	v_mul_f32_e32 v27, v168, v6
	v_mul_f32_e32 v28, v169, v7
	v_cvt_pk_bf16_f32 v49, v27, v28
	global_store_dwordx2 v247, v[48:49], s[88:89] offset:256
	v_mul_f32_e32 v27, v180, v8
	v_mul_f32_e32 v28, v181, v9
	v_cvt_pk_bf16_f32 v30, v27, v28
	v_mul_f32_e32 v27, v182, v10
	v_mul_f32_e32 v28, v183, v11
	v_cvt_pk_bf16_f32 v31, v27, v28
	global_store_dwordx2 v24, v[30:31], s[88:89]
	v_mul_f32_e32 v27, v166, v0
	v_mul_f32_e32 v28, v167, v1
	v_cvt_pk_bf16_f32 v48, v27, v28
	v_mul_f32_e32 v27, v168, v2
	v_mul_f32_e32 v28, v169, v3
	v_cvt_pk_bf16_f32 v49, v27, v28
	global_store_dwordx2 v24, v[48:49], s[88:89] offset:256
	v_mul_f32_e32 v50, v13, v13
	v_mul_f32_e32 v29, v15, v15
	v_fmac_f32_e32 v50, v12, v12
	v_fmac_f32_e32 v29, v14, v14
	v_add_f32_e32 v50, v50, v29
	v_mul_f32_e32 v51, v9, v9
	v_mul_f32_e32 v29, v11, v11
	v_fmac_f32_e32 v51, v8, v8
	v_fmac_f32_e32 v29, v10, v10
	v_add_f32_e32 v51, v51, v29
	v_mul_f32_e32 v52, v5, v5
	v_mul_f32_e32 v29, v7, v7
	v_fmac_f32_e32 v52, v4, v4
	v_fmac_f32_e32 v29, v6, v6
	v_add_f32_e32 v52, v52, v29
	v_mul_f32_e32 v53, v1, v1
	v_mul_f32_e32 v29, v3, v3
	v_fmac_f32_e32 v53, v0, v0
	v_fmac_f32_e32 v29, v2, v2
	v_add_f32_e32 v53, v53, v29
	v_add_f32_dpp v27, v50, v50 row_ror:8 row_mask:0xf bank_mask:0x3
	v_add_f32_dpp v28, v52, v52 row_ror:8 row_mask:0xf bank_mask:0x3
	v_add_f32_dpp v27, v51, v51 row_ror:8 row_mask:0xf bank_mask:0xc
	v_add_f32_dpp v28, v53, v53 row_ror:8 row_mask:0xf bank_mask:0xc
	v_add_f32_e32 v27, v27, v28
	ds_bpermute_b32 v29, v54, v27
	s_waitcnt lgkmcnt(0)
	v_add_f32_e32 v27, v27, v29
	ds_bpermute_b32 v29, v55, v27
	s_waitcnt lgkmcnt(0)
	v_add_f32_e32 v27, v27, v29
	s_and_saveexec_b64 s[14:15], s[42:43]
	ds_write_b32 v176, v27 offset:2816
	s_or_b64 exec, exec, s[14:15]
	s_waitcnt lgkmcnt(0)
	s_barrier
	s_mov_b64 s[14:15], exec
	v_readlane_b32 s4, v246, 6
	v_readlane_b32 s5, v246, 7
	s_and_b64 s[4:5], s[14:15], s[4:5]
	s_mov_b64 exec, s[4:5]
	s_cbranch_execz .LBB0_804
	s_waitcnt lgkmcnt(0)
	ds_read_b128 v[0:3], v189
	s_ashr_i32 s57, s56, 31
	s_ashr_i32 s47, s46, 31
	s_lshl_b64 s[4:5], s[56:57], 16
	v_readlane_b32 s16, v246, 4
	v_readlane_b32 s17, v246, 5
	s_add_u32 s16, s16, s4
	s_addc_u32 s17, s17, s5
	s_lshl_b64 s[4:5], s[46:47], 2
	s_waitcnt lgkmcnt(0)
	v_mov_b32_e32 v4, v1
	v_mov_b32_e32 v5, v2
	v_mov_b32_e32 v1, v3
	s_add_u32 s4, s16, s4
	v_pk_add_f32 v[0:1], v[4:5], v[0:1]
	s_addc_u32 s5, s17, s5
	v_add_f32_e32 v2, v0, v1
	v_lshl_add_u64 v[0:1], v[178:179], 2, s[4:5]
	global_store_dword v[0:1], v2, off

; #define LAS __attribute__((address_space(3)))
; __global__ void __launch_bounds__(512) hymba_fwd(Args a) {
;     extern __shared__ __attribute__((aligned(16))) unsigned char lds_raw[];
;     LAS unsigned char* lds = (LAS unsigned char*)lds_raw;
	.amdhsa_kernel _Z9hymba_fwd4Args
		.amdhsa_group_segment_fixed_size 0
		.amdhsa_private_segment_fixed_size 0
		.amdhsa_kernarg_size 400
		.amdhsa_user_sgpr_count 2
		.amdhsa_user_sgpr_dispatch_ptr 0
		.amdhsa_user_sgpr_queue_ptr 0
		.amdhsa_user_sgpr_kernarg_segment_ptr 1
		.amdhsa_user_sgpr_dispatch_id 0
		.amdhsa_user_sgpr_kernarg_preload_length 0
		.amdhsa_user_sgpr_kernarg_preload_offset 0
		.amdhsa_user_sgpr_private_segment_size 0
		.amdhsa_uses_dynamic_stack 0
		.amdhsa_enable_private_segment 0
		.amdhsa_system_sgpr_workgroup_id_x 1
		.amdhsa_system_sgpr_workgroup_id_y 0
		.amdhsa_system_sgpr_workgroup_id_z 0
		.amdhsa_system_sgpr_workgroup_info 0
		.amdhsa_system_vgpr_workitem_id 2
		.amdhsa_next_free_vgpr 248
		.amdhsa_next_free_sgpr 98
		.amdhsa_accum_offset 248
		.amdhsa_reserve_vcc 1
		.amdhsa_float_round_mode_32 0
		.amdhsa_float_round_mode_16_64 0
		.amdhsa_float_denorm_mode_32 3
		.amdhsa_float_denorm_mode_16_64 3
		.amdhsa_dx10_clamp 1
		.amdhsa_ieee_mode 1
		.amdhsa_fp16_overflow 0
		.amdhsa_tg_split 0
		.amdhsa_exception_fp_ieee_invalid_op 0
		.amdhsa_exception_fp_denorm_src 0
		.amdhsa_exception_fp_ieee_div_zero 0
		.amdhsa_exception_fp_ieee_overflow 0
		.amdhsa_exception_fp_ieee_underflow 0
		.amdhsa_exception_fp_ieee_inexact 0
		.amdhsa_exception_int_div_zero 0
	.end_amdhsa_kernel

; #define LAS __attribute__((address_space(3)))
; __global__ void __launch_bounds__(512) hymba_fwd(Args a) {
;     extern __shared__ __attribute__((aligned(16))) unsigned char lds_raw[];
;     LAS unsigned char* lds = (LAS unsigned char*)lds_raw;
amdhsa.kernels:
  - .agpr_count:     0
    .args:
      - .offset:         0
        .size:           144
        .value_kind:     by_value
      - .offset:         144
        .size:           4
        .value_kind:     hidden_block_count_x
      - .offset:         148
        .size:           4
        .value_kind:     hidden_block_count_y
      - .offset:         152
        .size:           4
        .value_kind:     hidden_block_count_z
      - .offset:         156
        .size:           2
        .value_kind:     hidden_group_size_x
      - .offset:         158
        .size:           2
        .value_kind:     hidden_group_size_y
      - .offset:         160
        .size:           2
        .value_kind:     hidden_group_size_z
      - .offset:         162
        .size:           2
        .value_kind:     hidden_remainder_x
      - .offset:         164
        .size:           2
        .value_kind:     hidden_remainder_y
      - .offset:         166
        .size:           2
        .value_kind:     hidden_remainder_z
      - .offset:         184
        .size:           8
        .value_kind:     hidden_global_offset_x
      - .offset:         192
        .size:           8
        .value_kind:     hidden_global_offset_y
      - .offset:         200
        .size:           8
        .value_kind:     hidden_global_offset_z
      - .offset:         208
        .size:           2
        .value_kind:     hidden_grid_dims
      - .offset:         232
        .size:           8
        .value_kind:     hidden_multigrid_sync_arg
      - .offset:         264
        .size:           4
        .value_kind:     hidden_dynamic_lds_size
    .group_segment_fixed_size: 0
    .kernarg_segment_align: 8
    .kernarg_segment_size: 400
    .language:       OpenCL C
    .language_version:
      - 2
      - 0
    .max_flat_workgroup_size: 512
    .name:           _Z9hymba_fwd4Args
    .private_segment_fixed_size: 0
    .sgpr_count:     104
    .sgpr_spill_count: 193
    .symbol:         _Z9hymba_fwd4Args.kd
    .uniform_work_group_size: 1
    .uses_dynamic_stack: false
    .vgpr_count:     248
    .vgpr_spill_count: 0
    .wavefront_size: 64
